# attention bias-table staging: 8 loads per thread issued together, one wait (was a ladder of dependent load/wait/write rounds)
# baseline (speedup 1.0000x reference)
; #define LAS __attribute__((address_space(3)))
; __device__ __forceinline__ void attn_all(KArgs& a, LAS unsigned char* lds, int l) {
;     ...
;     LAS float* rpb_s = (LAS float*)(lds + 1024);
;     for (int i = tid; i < 3720; i += 512) rpb_s[i] = a.na_rpb[l * 3720 + i] * 1.44269504f;
.LBB0_477:
	v_mov_b32_e32 v2, v216
	s_movk_i32 s0, 0xe88
	s_nop 0
	v_readfirstlane_b32 s6, v2
	v_cmp_gt_i32_e32 vcc, s0, v2
	s_and_saveexec_b64 s[0:1], vcc
	s_cbranch_execz .LBB0_490
	s_load_dwordx2 s[4:5], s[4:5], 0xa0
	s_mul_i32 s8, s2, 0xe88
	v_add_u32_e32 v0, s8, v2
	v_lshlrev_b32_e32 v0, 2, v0
	v_lshlrev_b32_e32 v3, 2, v2
	v_add_u32_e32 v6, 0x1000, v0
	v_add_u32_e32 v13, 0x2000, v0
	v_cmp_gt_u32_e32 vcc, 0x88, v2
	s_waitcnt lgkmcnt(0)
	global_load_dword v4, v0, s[4:5]
	global_load_dword v5, v0, s[4:5] offset:2048
	global_load_dword v7, v6, s[4:5]
	global_load_dword v8, v6, s[4:5] offset:2048
	v_add_u32_e32 v6, 0x3000, v0
	global_load_dword v9, v13, s[4:5]
	global_load_dword v10, v13, s[4:5] offset:2048
	global_load_dword v11, v6, s[4:5]
	s_and_saveexec_b64 s[8:9], vcc
	global_load_dword v12, v6, s[4:5] offset:2048
	s_waitcnt vmcnt(0)
	v_mul_f32_e32 v12, 0x3fb8aa3b, v12
	ds_write_b32 v3, v12 offset:15360
	s_or_b64 exec, exec, s[8:9]
	s_waitcnt vmcnt(0)
	v_mul_f32_e32 v4, 0x3fb8aa3b, v4
	v_mul_f32_e32 v5, 0x3fb8aa3b, v5
	v_mul_f32_e32 v7, 0x3fb8aa3b, v7
	v_mul_f32_e32 v8, 0x3fb8aa3b, v8
	v_mul_f32_e32 v9, 0x3fb8aa3b, v9
	v_mul_f32_e32 v10, 0x3fb8aa3b, v10
	v_mul_f32_e32 v11, 0x3fb8aa3b, v11
	ds_write_b32 v3, v4 offset:1024
	ds_write_b32 v3, v5 offset:3072
	ds_write_b32 v3, v7 offset:5120
	ds_write_b32 v3, v8 offset:7168
	ds_write_b32 v3, v9 offset:9216
	ds_write_b32 v3, v10 offset:11264
	ds_write_b32 v3, v11 offset:13312
